# v11 plus static prompt-attention unit assignment (one batch-head per non-decode workgroup, all eight query blocks, no queue atomics)
# baseline (speedup 1.0000x reference)
.LBB0_785:
	s_cmp_lt_i32 s96, 5
	s_cselect_b64 s[4:5], -1, 0
	s_cmp_gt_i32 s97, 4
	s_cselect_b64 s[6:7], -1, 0
	s_and_b64 s[4:5], s[4:5], s[6:7]
	s_andn2_b64 vcc, exec, s[4:5]
	s_cbranch_vccnz .LBB0_1063
	s_lshr_b32 s101, s2, 4
	s_lshl_b32 s101, s101, 3
	s_and_b32 s100, s2, 7
	s_or_b32 s101, s101, s100
	s_bitcmp0_b32 s2, 3
	s_cselect_b32 s100, s101, 0x80
	s_cselect_b32 s101, 0x408, s101
	s_and_b32 s10, s95, 0xffffffc0
	s_bfe_u32 s8, s95, 0x10006
	s_add_u32 s30, s38, 0x12300000
	s_addc_u32 s31, s39, 0
	s_mov_b32 s5, 0
	s_add_u32 s52, s38, 0x100000
	s_mul_i32 s4, s92, 0x60
	s_addc_u32 s53, s39, 0
	s_lshl_b64 s[4:5], s[4:5], 1
	s_add_u32 s56, s30, s4
	s_addc_u32 s57, s31, s5
	s_ashr_i32 s11, s10, 31
	s_lshr_b32 s5, s95, 7
	s_cmpk_lt_u32 s95, 0x80
	s_cselect_b64 s[58:59], -1, 0
	s_lshl_b32 s14, s5, 13
	s_mul_i32 s9, s92, 0x1200
	s_add_i32 s84, 0, 0x22000
	s_mul_i32 s12, s8, 0x1200
	s_add_i32 s83, 0, 0x22900
	s_lshr_b32 s13, s95, 4
	s_and_b32 s15, s14, 0x7fffc000
	s_lshl_b32 s78, s8, 5
	s_add_i32 s45, s84, s9
	s_lshl_b32 s3, s92, 5
	s_add_i32 s76, s83, s12
	s_add_i32 s77, s15, 0
	s_and_b32 s79, s13, 8
	s_or_b32 s80, s78, 8
	s_or_b32 s81, s78, 16
	s_or_b32 s82, s78, 24
	s_add_i32 s83, s83, s9
	s_add_i32 s84, s84, s12
	s_add_u32 s60, s38, 0x10f00000
	s_addc_u32 s61, s39, 0
	s_add_u32 s54, s38, 0x12000000
	s_addc_u32 s55, s39, 0
	s_lshl_b32 s9, s92, 8
	s_add_i32 s88, s9, 0
	v_mbcnt_hi_u32_b32 v187, -1, v254
	s_add_i32 s85, s77, 0x17400
	s_add_i32 s86, s14, 0
	s_add_i32 s87, s88, 0x24400
	s_add_i32 s88, s88, 0x16000
	s_and_b32 s12, 64, s95
	v_writelane_b32 v255, s90, 6
	v_and_b32_e32 v1, 64, v187
	s_cmp_eq_u32 s8, 0
	v_writelane_b32 v255, s91, 7
	s_mul_i32 s4, s92, 0x250
	v_xor_b32_e32 v0, 32, v187
	v_add_u32_e32 v188, 64, v1
	s_cselect_b64 s[8:9], -1, 0
	s_cmp_lg_u32 s12, 0
	v_cmp_lt_i32_e32 vcc, v0, v188
	v_writelane_b32 v255, s95, 8
	s_cselect_b64 s[62:63], -1, 0
	s_add_i32 s90, s4, 0
	s_mul_i32 s4, s92, 0x410
	v_add_u32_e32 v186, s10, v187
	v_cndmask_b32_e32 v0, v187, v0, vcc
	s_lshl_b32 s5, s5, 8
	v_writelane_b32 v255, s92, 5
	s_add_i32 s92, s4, 0
	s_add_i32 s93, 0, 0x21140
	v_lshlrev_b32_e32 v189, 2, v0
	v_cmp_eq_u32_e64 s[6:7], 0, v186
	s_add_i32 s89, s5, 0
	s_lshl_b64 s[64:65], s[10:11], 2
	s_add_i32 s91, s10, 0x200
	s_addk_i32 s92, 0x4c00
	v_mov_b32_e32 v121, 0
	s_mov_b32 s94, 0x8000
	s_movk_i32 s95, 0x600
	s_movk_i32 s96, 0x7fff
	s_movk_i32 s97, 0x50
	s_movk_i32 s50, 0x4000
	s_movk_i32 s51, 0x2000
	s_movk_i32 s4, 0x6000
	s_mov_b32 s5, 0xa000
	s_mov_b32 s48, 0xc000
	s_mov_b32 s49, 0xe000
	s_mov_b32 s74, 0x41000000
	s_lshl_b64 s[66:67], s[10:11], 1
	s_mov_b64 s[68:69], 0x19700400
	s_mov_b32 s75, 0x19700000
	v_mov_b32_e32 v123, s93
	v_mov_b32_e32 v138, 0xff800000
	s_branch .LBB0_789

.LBB0_868:
	s_and_saveexec_b64 s[8:9], s[6:7]
	s_cbranch_execz .LBB0_872
	s_mov_b64 s[12:13], exec
	v_mbcnt_lo_u32_b32 v0, s12, 0
	v_mbcnt_hi_u32_b32 v0, s13, v0
	v_cmp_eq_u32_e32 vcc, 0, v0
	s_and_saveexec_b64 s[10:11], vcc
	s_cbranch_execz .LBB0_871
	s_bcnt1_i32_b64 s12, s[12:13]
	v_mov_b32_e32 v1, s12
	s_cmpk_lg_u32 s44, 0x100
	s_cbranch_scc1 .Lmy_pq_dyn
	v_mov_b32_e32 v1, s101
	s_add_i32 s99, s101, 0x80
	s_cmpk_lt_i32 s99, 0x400
	s_cbranch_scc1 .Lmy_pq_keep
	s_cmpk_ge_i32 s101, 0x400
	s_cbranch_scc1 .Lmy_pq_none
	s_and_b32 s99, s101, 0x7f
	s_cmpk_lt_u32 s99, 8
	s_cbranch_scc0 .Lmy_pq_none
	s_addk_i32 s99, 0x400
	s_branch .Lmy_pq_keep
.Lmy_pq_none:
	s_movk_i32 s99, 0x408
.Lmy_pq_keep:
	s_mov_b32 s101, s99
	s_branch .LBB0_871
.Lmy_pq_dyn:
	global_atomic_add v1, v177, v1, s[38:39] offset:512 sc0
